# MLA lazy-rescale test shortened: scalar branch on the all-lanes-below-threshold result, alpha=1 fast path; new-max / alpha candidate math (v_max, v_sub, v_mul, v_exp) moved into the rarely taken resca
# speedup vs baseline: 1.0112x; 1.0112x over previous
; __device__ __forceinline__ void partialSM(f32x16& p0, f32x16& p1, float& m_reg, float& mn, float& alpha) {
;   constexpr float C = SCALE * 1.4426950408889634f;
;   float pmax = p0[0];
; #pragma unroll
;   for (int r = 1; r < 16; ++r) pmax = fmaxf(pmax, p0[r]);
; #pragma unroll
;   for (int r = 0; r < 16; ++r) pmax = fmaxf(pmax, p1[r]);
;   { auto rr = __builtin_amdgcn_permlane32_swap(__float_as_uint(pmax), __float_as_uint(pmax), false, false);
;     pmax = fmaxf(__uint_as_float(rr[0]), __uint_as_float(rr[1])); }
;   if (__builtin_expect(__all(pmax - m_reg <= THR / SCALE), 1)) { mn = m_reg; alpha = 1.f; }
;   else { mn = fmaxf(m_reg, pmax); alpha = __builtin_amdgcn_exp2f((m_reg - mn) * C); m_reg = mn; }
;   float mnC = -mn * C;
; #pragma unroll
;   for (int r = 0; r < 16; ++r) p0[r] = fmaf(p0[r], C, mnC);
; #pragma unroll
;   for (int r = 0; r < 16; ++r) p1[r] = fmaf(p1[r], C, mnC);
; #pragma unroll
;   for (int r = 0; r < 16; ++r) p0[r] = __builtin_amdgcn_exp2f(p0[r]);
; }
; __device__ __forceinline__ void finishSM(f32x16& p0, f32x16& p1, float alpha, float& l_reg, bf16x8& pa0, bf16x8& pa1, bf16x8& pa2, bf16x8& pa3) {
; #pragma unroll
;   for (int r = 0; r < 16; ++r) p1[r] = __builtin_amdgcn_exp2f(p1[r]);
;   float ps = 0;
; #pragma unroll
;   for (int r = 0; r < 16; ++r) ps += p0[r];
; #pragma unroll
;   for (int r = 0; r < 16; ++r) ps += p1[r];
;   { auto rr = __builtin_amdgcn_permlane32_swap(__float_as_uint(ps), __float_as_uint(ps), false, false);
;     ps = __uint_as_float(rr[0]) + __uint_as_float(rr[1]); }
;   l_reg = l_reg * alpha + ps;
;     ...
;   PK4(p0, 0, pa0); PK4(p0, 8, pa1); PK4(p1, 0, pa2); PK4(p1, 8, pa3);
;     ...
; }
.Lback0_b:
	v_max3_f32 v144, v64, v65, v66
	v_max3_f32 v145, v80, v81, v82
	v_max3_f32 v144, v144, v67, v68
	v_max3_f32 v145, v145, v83, v84
	v_max3_f32 v144, v144, v69, v70
	v_max3_f32 v145, v145, v85, v86
	v_max3_f32 v144, v144, v71, v72
	v_max3_f32 v145, v145, v87, v88
	v_max3_f32 v144, v144, v73, v74
	v_max3_f32 v145, v145, v89, v90
	v_max3_f32 v144, v144, v75, v76
	v_max3_f32 v145, v145, v91, v92
	v_max3_f32 v144, v144, v77, v78
	v_max3_f32 v145, v145, v93, v94
	v_max3_f32 v144, v144, v79, v95
	v_max_f32_e32 v144, v144, v145
	v_mov_b32_e32 v145, v144
	s_nop 1
	v_permlane32_swap_b32_e32 v144, v145
	v_max_f32_e32 v144, v144, v145
	v_sub_f32_e32 v145, v144, v220
	v_cmp_ge_f32_e32 vcc, s30, v145
	s_cmp_eq_u64 vcc, exec
	s_cselect_b64 s[8:9], -1, 0
	s_waitcnt lgkmcnt(0)
	s_barrier
	v_mov_b32_e32 v222, v76
	v_mov_b32_e32 v223, v77
	v_mov_b32_e32 v76, v90
	v_mov_b32_e32 v77, v91
	v_mov_b32_e32 v226, v72
	v_mov_b32_e32 v227, v73
	v_mov_b32_e32 v224, v74
	v_mov_b32_e32 v225, v75
	v_mov_b32_e32 v74, v92
	v_mov_b32_e32 v75, v93
	v_mov_b32_e32 v73, v94
	v_mov_b32_e32 v72, v95
	s_cbranch_scc0 .Lslow_b0
	v_mov_b32_e32 v221, 1.0
.Lafter_b0:
	v_mul_f32_e32 v90, 0xbdd53b94, v220
	v_fmamk_f32 v64, v64, 0x3dd53b94, v90
	v_fmamk_f32 v65, v65, 0x3dd53b94, v90
	v_exp_f32_e32 v64, v64
	v_fmamk_f32 v66, v66, 0x3dd53b94, v90
	v_exp_f32_e32 v65, v65
	v_fmamk_f32 v67, v67, 0x3dd53b94, v90
	v_exp_f32_e32 v66, v66
	v_fmamk_f32 v68, v68, 0x3dd53b94, v90
	v_fmamk_f32 v73, v73, 0x3dd53b94, v90
	v_exp_f32_e32 v67, v67
	v_fmamk_f32 v69, v69, 0x3dd53b94, v90
	v_fmamk_f32 v92, v227, 0x3dd53b94, v90
	v_exp_f32_e32 v68, v68
	v_exp_f32_e32 v227, v73
	v_add_f32_e32 v73, 0, v64
	v_fmamk_f32 v70, v70, 0x3dd53b94, v90
	v_exp_f32_e32 v69, v69
	v_add_f32_e32 v73, v65, v73
	v_fmamk_f32 v71, v71, 0x3dd53b94, v90
	v_exp_f32_e32 v70, v70
	v_add_f32_e32 v73, v66, v73
	v_fmamk_f32 v91, v226, 0x3dd53b94, v90
	v_exp_f32_e32 v71, v71
	v_add_f32_e32 v73, v67, v73
	v_fmamk_f32 v93, v224, 0x3dd53b94, v90
	v_fmamk_f32 v94, v225, 0x3dd53b94, v90
	v_fmamk_f32 v95, v222, 0x3dd53b94, v90
	v_fmamk_f32 v222, v223, 0x3dd53b94, v90
	v_fmamk_f32 v78, v78, 0x3dd53b94, v90
	v_fmamk_f32 v79, v79, 0x3dd53b94, v90
	v_fmamk_f32 v80, v80, 0x3dd53b94, v90
	v_fmamk_f32 v81, v81, 0x3dd53b94, v90
	v_fmamk_f32 v82, v82, 0x3dd53b94, v90
	v_fmamk_f32 v83, v83, 0x3dd53b94, v90
	v_fmamk_f32 v84, v84, 0x3dd53b94, v90
	v_fmamk_f32 v85, v85, 0x3dd53b94, v90
	v_fmamk_f32 v86, v86, 0x3dd53b94, v90
	v_fmamk_f32 v87, v87, 0x3dd53b94, v90
	v_fmamk_f32 v88, v88, 0x3dd53b94, v90
	v_fmamk_f32 v89, v89, 0x3dd53b94, v90
	v_fmamk_f32 v76, v76, 0x3dd53b94, v90
	v_fmamk_f32 v77, v77, 0x3dd53b94, v90
	v_fmamk_f32 v74, v74, 0x3dd53b94, v90
	v_fmamk_f32 v75, v75, 0x3dd53b94, v90
	v_fmac_f32_e32 v90, 0x3dd53b94, v72
	v_exp_f32_e32 v72, v91
	v_add_f32_e32 v73, v68, v73
	v_exp_f32_e32 v91, v92
	v_add_f32_e32 v73, v69, v73
	v_exp_f32_e32 v92, v93
	v_add_f32_e32 v73, v70, v73
	v_exp_f32_e32 v93, v94
	v_add_f32_e32 v73, v71, v73
	v_exp_f32_e32 v94, v95
	v_add_f32_e32 v73, v72, v73
	v_exp_f32_e32 v95, v222
	v_add_f32_e32 v73, v91, v73
	v_exp_f32_e32 v78, v78
	v_add_f32_e32 v73, v92, v73
	v_exp_f32_e32 v79, v79
	v_add_f32_e32 v73, v93, v73
	v_exp_f32_e32 v80, v80
	v_add_f32_e32 v73, v94, v73
	v_exp_f32_e32 v81, v81
	v_add_f32_e32 v73, v95, v73
	v_exp_f32_e32 v82, v82
	v_add_f32_e32 v73, v78, v73
	v_exp_f32_e32 v83, v83
	v_add_f32_e32 v73, v79, v73
	v_exp_f32_e32 v84, v84
	v_add_f32_e32 v73, v80, v73
	v_exp_f32_e32 v85, v85
	v_add_f32_e32 v73, v81, v73
	v_exp_f32_e32 v86, v86
	v_add_f32_e32 v73, v82, v73
	v_exp_f32_e32 v87, v87
	v_add_f32_e32 v73, v83, v73
	v_exp_f32_e32 v88, v88
	v_add_f32_e32 v73, v84, v73
	v_exp_f32_e32 v89, v89
	v_add_f32_e32 v73, v85, v73
	v_exp_f32_e32 v224, v76
	v_add_f32_e32 v73, v86, v73
	v_exp_f32_e32 v77, v77
	v_add_f32_e32 v73, v87, v73
	v_exp_f32_e32 v225, v74
	v_add_f32_e32 v73, v88, v73
	v_exp_f32_e32 v226, v75
	v_add_f32_e32 v73, v89, v73
	v_add_f32_e32 v73, v224, v73
	v_exp_f32_e32 v90, v90
	v_add_f32_e32 v73, v77, v73
	v_add_f32_e32 v73, v225, v73
	v_add_f32_e32 v73, v226, v73
	v_add_f32_e32 v73, v227, v73
	v_add_f32_e32 v222, v90, v73
	v_mov_b32_e32 v223, v222
	s_nop 1
	v_permlane32_swap_b32_e32 v222, v223
	v_cvt_pk_bf16_f32 v64, v64, v65
	v_cvt_pk_bf16_f32 v65, v66, v67
	v_cvt_pk_bf16_f32 v66, v68, v69
	v_cvt_pk_bf16_f32 v67, v70, v71
	v_cvt_pk_bf16_f32 v68, v72, v91
	v_cvt_pk_bf16_f32 v69, v92, v93
	v_cvt_pk_bf16_f32 v70, v94, v95
	v_cvt_pk_bf16_f32 v71, v78, v79
	v_cvt_pk_bf16_f32 v72, v80, v81
	v_cvt_pk_bf16_f32 v73, v82, v83
	v_cvt_pk_bf16_f32 v74, v84, v85
	v_cvt_pk_bf16_f32 v75, v86, v87
	v_cvt_pk_bf16_f32 v76, v88, v89
	v_cvt_pk_bf16_f32 v77, v224, v77
	v_cvt_pk_bf16_f32 v78, v225, v226
	v_cvt_pk_bf16_f32 v79, v227, v90
	s_nop 0
	v_permlane32_swap_b32_e32 v64, v66
	v_permlane32_swap_b32_e32 v65, v67
	v_permlane32_swap_b32_e32 v68, v70
	v_permlane32_swap_b32_e32 v69, v71
	v_permlane32_swap_b32_e32 v72, v74
	v_permlane32_swap_b32_e32 v73, v75
	v_permlane32_swap_b32_e32 v76, v78
	v_permlane32_swap_b32_e32 v77, v79
	ds_read_b64_tr_b16 v[80:81], v206 offset:0
	ds_read_b64_tr_b16 v[82:83], v206 offset:0x800
	ds_read_b64_tr_b16 v[84:85], v206 offset:0x1000
	ds_read_b64_tr_b16 v[86:87], v206 offset:0x1800
	ds_read_b64_tr_b16 v[88:89], v206 offset:0x2000
	ds_read_b64_tr_b16 v[90:91], v206 offset:0x2800
	ds_read_b64_tr_b16 v[92:93], v206 offset:0x3000
	ds_read_b64_tr_b16 v[94:95], v206 offset:0x3800
	ds_read_b64_tr_b16 v[224:225], v206 offset:0x200
	ds_read_b64_tr_b16 v[226:227], v206 offset:0xa00
	ds_read_b64_tr_b16 v[228:229], v206 offset:0x1200
	ds_read_b64_tr_b16 v[230:231], v206 offset:0x1a00
	ds_read_b64_tr_b16 v[232:233], v206 offset:0x2200
	ds_read_b64_tr_b16 v[234:235], v206 offset:0x2a00
	ds_read_b64_tr_b16 v[236:237], v206 offset:0x3200
	ds_read_b64_tr_b16 v[238:239], v206 offset:0x3a00
	s_waitcnt lgkmcnt(8)
; #define SBAR() __builtin_amdgcn_sched_barrier(0)
; __device__ __forceinline__ void qkt2(f32x16& p0, f32x16& p1, const char* Ks, const bf16x8* qr, const int* kb4) {
;     ...
;   p0 = f32x16{}; p1 = f32x16{};
;   bf16x8 a0 = KLD(0, 0), b0 = KLD(0, 1), a1 = KLD(1, 0), b1 = KLD(1, 1), a2, b2;
;     ...
;   QSTEP(0, a0, b0, a2, b2); QSTEP(1, a1, b1, a0, b0); QSTEP(2, a2, b2, a1, b1);
;   QSTEP(3, a0, b0, a2, b2); QSTEP(4, a1, b1, a0, b0); QSTEP(5, a2, b2, a1, b1);
;   QSTEP(6, a0, b0, a2, b2); QSTEP(7, a1, b1, a0, b0); QSTEP(8, a2, b2, a1, b1);
;   QSTEP(9, a0, b0, a2, b2); QSTEP(10, a1, b1, a0, b0); QSTEP(11, a2, b2, a1, b1);
;     ...
; }
; template <int D0> __device__ __forceinline__ void v_issue(VSet& s, int vb) {
;   s.l0 = tr_read<v_rd_off(D0, 0, 0)>(vb); s.h0 = tr_read<v_rd_off(D0, 0, 1)>(vb); s.l1 = tr_read<v_rd_off(D0, 1, 0)>(vb); s.h1 = tr_read<v_rd_off(D0, 1, 1)>(vb);
;   s.l2 = tr_read<v_rd_off(D0, 2, 0)>(vb); s.h2 = tr_read<v_rd_off(D0, 2, 1)>(vb); s.l3 = tr_read<v_rd_off(D0, 3, 0)>(vb); s.h3 = tr_read<v_rd_off(D0, 3, 1)>(vb);
; }
; __device__ __forceinline__ void v_mma(f32x16& od, VSet& s, bf16x8 pa0, bf16x8 pa1, bf16x8 pa2, bf16x8 pa3) {
;   asm volatile("" : "+v"(s.l0), "+v"(s.h0), "+v"(s.l1), "+v"(s.h1), "+v"(s.l2), "+v"(s.h2), "+v"(s.l3), "+v"(s.h3));
;     ...
;   od = __builtin_amdgcn_mfma_f32_32x32x16_bf16(pa0, PK(s.l0, s.h0), od, 0, 0, 0);
;   od = __builtin_amdgcn_mfma_f32_32x32x16_bf16(pa1, PK(s.l1, s.h1), od, 0, 0, 0);
;   od = __builtin_amdgcn_mfma_f32_32x32x16_bf16(pa2, PK(s.l2, s.h2), od, 0, 0, 0);
;   od = __builtin_amdgcn_mfma_f32_32x32x16_bf16(pa3, PK(s.l3, s.h3), od, 0, 0, 0);
;     ...
; }
; __device__ __forceinline__ void pv2(f32x16* o, int vb, bf16x8 pa0, bf16x8 pa1, bf16x8 pa2, bf16x8 pa3) {
;   VSet X, Y;
;   SBAR(); v_issue<0>(X, vb); v_issue<1>(Y, vb);
;   asm volatile("s_waitcnt lgkmcnt(8)" ::: "memory"); SBAR(); v_mma(o[0], X, pa0, pa1, pa2, pa3); SBAR();
;   v_issue<2>(X, vb);
;   asm volatile("s_waitcnt lgkmcnt(8)" ::: "memory"); SBAR(); v_mma(o[1], Y, pa0, pa1, pa2, pa3); SBAR();
;   v_issue<3>(Y, vb);
;   asm volatile("s_waitcnt lgkmcnt(8)" ::: "memory"); SBAR(); v_mma(o[2], X, pa0, pa1, pa2, pa3); SBAR();
;   asm volatile("s_waitcnt lgkmcnt(0)" ::: "memory"); SBAR(); v_mma(o[3], Y, pa0, pa1, pa2, pa3); SBAR();
; }
	s_nop 0
	s_nop 0
	v_mfma_f32_32x32x16_bf16 v[0:15], v[64:67], v[80:83], v[0:15]
	v_mfma_f32_32x32x16_bf16 v[0:15], v[68:71], v[84:87], v[0:15]
	v_mfma_f32_32x32x16_bf16 v[0:15], v[72:75], v[88:91], v[0:15]
	v_mfma_f32_32x32x16_bf16 v[0:15], v[76:79], v[92:95], v[0:15]
	ds_read_b64_tr_b16 v[80:81], v206 offset:0x400
	ds_read_b64_tr_b16 v[82:83], v206 offset:0xc00
	ds_read_b64_tr_b16 v[84:85], v206 offset:0x1400
	ds_read_b64_tr_b16 v[86:87], v206 offset:0x1c00
	ds_read_b64_tr_b16 v[88:89], v206 offset:0x2400
	ds_read_b64_tr_b16 v[90:91], v206 offset:0x2c00
	ds_read_b64_tr_b16 v[92:93], v206 offset:0x3400
	ds_read_b64_tr_b16 v[94:95], v206 offset:0x3c00
	s_waitcnt lgkmcnt(8)
	s_nop 0
	v_mfma_f32_32x32x16_bf16 v[48:63], v[64:67], v[224:227], v[48:63]
	v_mfma_f32_32x32x16_bf16 v[48:63], v[68:71], v[228:231], v[48:63]
	v_mfma_f32_32x32x16_bf16 v[48:63], v[72:75], v[232:235], v[48:63]
	v_mfma_f32_32x32x16_bf16 v[48:63], v[76:79], v[236:239], v[48:63]
	ds_read_b64_tr_b16 v[224:225], v206 offset:0x600
	ds_read_b64_tr_b16 v[226:227], v206 offset:0xe00
	ds_read_b64_tr_b16 v[228:229], v206 offset:0x1600
	ds_read_b64_tr_b16 v[230:231], v206 offset:0x1e00
	ds_read_b64_tr_b16 v[232:233], v206 offset:0x2600
	ds_read_b64_tr_b16 v[234:235], v206 offset:0x2e00
	ds_read_b64_tr_b16 v[236:237], v206 offset:0x3600
	ds_read_b64_tr_b16 v[238:239], v206 offset:0x3e00
	s_waitcnt lgkmcnt(8)
	s_nop 0
	v_mfma_f32_32x32x16_bf16 v[32:47], v[64:67], v[80:83], v[32:47]
	v_mfma_f32_32x32x16_bf16 v[32:47], v[68:71], v[84:87], v[32:47]
	v_mfma_f32_32x32x16_bf16 v[32:47], v[72:75], v[88:91], v[32:47]
	v_mfma_f32_32x32x16_bf16 v[32:47], v[76:79], v[92:95], v[32:47]
	s_waitcnt lgkmcnt(0)
	s_nop 0
	v_mfma_f32_32x32x16_bf16 v[16:31], v[64:67], v[224:227], v[16:31]
	v_mfma_f32_32x32x16_bf16 v[16:31], v[68:71], v[228:231], v[16:31]
	v_mfma_f32_32x32x16_bf16 v[16:31], v[72:75], v[232:235], v[16:31]
	v_mfma_f32_32x32x16_bf16 v[16:31], v[76:79], v[236:239], v[16:31]
	s_waitcnt lgkmcnt(0)
	s_barrier
	v_add_co_u32_e32 v144, vcc, 0x28780000, v196
	s_nop 1
	v_addc_co_u32_e32 v145, vcc, 0, v197, vcc
	v_add_co_u32_e32 v146, vcc, 0x1b360000, v194
	s_nop 1
	v_addc_co_u32_e32 v147, vcc, 0, v195, vcc
	ds_read_b128 v[64:67], v216 offset:12288
	ds_read_b128 v[194:197], v217 offset:12288
	ds_read_b128 v[224:227], v209 offset:57344
	ds_read_b128 v[228:231], v208 offset:57344
	ds_read_b128 v[68:71], v210 offset:57344
	ds_read_b128 v[232:235], v218 offset:12288
	s_waitcnt vmcnt(0)
	s_cmpk_gt_u32 s44, 0xfd
	s_waitcnt lgkmcnt(1)
	v_mfma_f32_32x32x16_bf16 v[80:95], v[68:71], v[96:99], 0
	v_mfma_f32_32x32x16_bf16 v[64:79], v[64:67], v[96:99], 0
	ds_write_b128 v212, v[164:167]
	ds_write_b128 v212, v[168:171] offset:1024
	ds_read_b128 v[236:239], v207 offset:57344
	ds_read_b128 v[240:243], v219 offset:12288
	v_mfma_f32_32x32x16_bf16 v[80:95], v[224:227], v[100:103], v[80:95]
	v_mfma_f32_32x32x16_bf16 v[64:79], v[194:197], v[100:103], v[64:79]
	ds_write_b128 v211, v[172:175] offset:32768
	ds_write_b128 v211, v[176:179] offset:32896
	ds_read_b128 v[194:197], v210 offset:57472
	ds_read_b128 v[224:227], v216 offset:12416
	s_cbranch_scc1 .Lb2_skip1
	global_load_dwordx4 v[164:167], v[144:145], off offset:256
	global_load_dwordx4 v[168:171], v[144:145], off offset:384

; #define QSTEP(d, A, B, NA, NB) do { if ((d) + 2 < 12) { NA = KLD((d) + 2, 0); NB = KLD((d) + 2, 1); } SBAR(); \
;     p0 = __builtin_amdgcn_mfma_f32_32x32x16_bf16(A, qr[d], p0, 0, 0, 0); p1 = __builtin_amdgcn_mfma_f32_32x32x16_bf16(B, qr[d], p1, 0, 0, 0); SBAR(); } while (0)
; __device__ __forceinline__ void partialSM(f32x16& p0, f32x16& p1, float& m_reg, float& mn, float& alpha) {
;   constexpr float C = SCALE * 1.4426950408889634f;
;   float pmax = p0[0];
; #pragma unroll
;   for (int r = 1; r < 16; ++r) pmax = fmaxf(pmax, p0[r]);
; #pragma unroll
;   for (int r = 0; r < 16; ++r) pmax = fmaxf(pmax, p1[r]);
;   { auto rr = __builtin_amdgcn_permlane32_swap(__float_as_uint(pmax), __float_as_uint(pmax), false, false);
;     pmax = fmaxf(__uint_as_float(rr[0]), __uint_as_float(rr[1])); }
;   if (__builtin_expect(__all(pmax - m_reg <= THR / SCALE), 1)) { mn = m_reg; alpha = 1.f; }
;   else { mn = fmaxf(m_reg, pmax); alpha = __builtin_amdgcn_exp2f((m_reg - mn) * C); m_reg = mn; }
;   float mnC = -mn * C;
; #pragma unroll
;   for (int r = 0; r < 16; ++r) p0[r] = fmaf(p0[r], C, mnC);
; #pragma unroll
;   for (int r = 0; r < 16; ++r) p1[r] = fmaf(p1[r], C, mnC);
; #pragma unroll
;   for (int r = 0; r < 16; ++r) p0[r] = __builtin_amdgcn_exp2f(p0[r]);
; }
; __device__ __forceinline__ void finishSM(f32x16& p0, f32x16& p1, float alpha, float& l_reg, bf16x8& pa0, bf16x8& pa1, bf16x8& pa2, bf16x8& pa3) {
; #pragma unroll
;   for (int r = 0; r < 16; ++r) p1[r] = __builtin_amdgcn_exp2f(p1[r]);
;   float ps = 0;
; #pragma unroll
;   for (int r = 0; r < 16; ++r) ps += p0[r];
; #pragma unroll
;   for (int r = 0; r < 16; ++r) ps += p1[r];
;   { auto rr = __builtin_amdgcn_permlane32_swap(__float_as_uint(ps), __float_as_uint(ps), false, false);
;     ps = __uint_as_float(rr[0]) + __uint_as_float(rr[1]); }
;   l_reg = l_reg * alpha + ps;
; __device__ __forceinline__ void qkt2(f32x16& p0, f32x16& p1, const char* Ks, const bf16x8* qr, const int* kb4) {
;     ...
;   QSTEP(0, a0, b0, a2, b2); QSTEP(1, a1, b1, a0, b0); QSTEP(2, a2, b2, a1, b1);
;   QSTEP(3, a0, b0, a2, b2); QSTEP(4, a1, b1, a0, b0); QSTEP(5, a2, b2, a1, b1);
;   QSTEP(6, a0, b0, a2, b2); QSTEP(7, a1, b1, a0, b0); QSTEP(8, a2, b2, a1, b1);
;   QSTEP(9, a0, b0, a2, b2); QSTEP(10, a1, b1, a0, b0); QSTEP(11, a2, b2, a1, b1);
.LBB0_447:
	s_waitcnt lgkmcnt(5)
	v_mfma_f32_32x32x16_bf16 v[80:95], v[194:197], v[112:115], v[80:95]
	v_mfma_f32_32x32x16_bf16 v[64:79], v[224:227], v[112:115], v[64:79]
	ds_read_b128 v[194:197], v207 offset:57472
	ds_read_b128 v[224:227], v219 offset:12416
	s_waitcnt lgkmcnt(4)
	v_mfma_f32_32x32x16_bf16 v[80:95], v[228:231], v[116:119], v[80:95]
	v_mfma_f32_32x32x16_bf16 v[64:79], v[232:235], v[116:119], v[64:79]
	ds_read_b128 v[228:231], v210 offset:57600
	ds_read_b128 v[232:235], v216 offset:12544
	s_waitcnt lgkmcnt(4)
	v_mfma_f32_32x32x16_bf16 v[80:95], v[236:239], v[120:123], v[80:95]
	v_mfma_f32_32x32x16_bf16 v[64:79], v[240:243], v[120:123], v[64:79]
	ds_read_b128 v[236:239], v209 offset:57600
	ds_read_b128 v[240:243], v217 offset:12544
	s_waitcnt lgkmcnt(4)
	v_mfma_f32_32x32x16_bf16 v[80:95], v[194:197], v[124:127], v[80:95]
	v_mfma_f32_32x32x16_bf16 v[64:79], v[224:227], v[124:127], v[64:79]
	ds_read_b128 v[194:197], v208 offset:57600
	ds_read_b128 v[224:227], v218 offset:12544
	s_waitcnt lgkmcnt(4)
	v_mfma_f32_32x32x16_bf16 v[80:95], v[228:231], v[132:135], v[80:95]
	v_mfma_f32_32x32x16_bf16 v[64:79], v[232:235], v[132:135], v[64:79]
	ds_read_b128 v[228:231], v207 offset:57600
	ds_read_b128 v[232:235], v219 offset:12544
	s_waitcnt lgkmcnt(4)
	v_mfma_f32_32x32x16_bf16 v[80:95], v[236:239], v[140:143], v[80:95]
	v_mfma_f32_32x32x16_bf16 v[64:79], v[240:243], v[140:143], v[64:79]
	s_waitcnt lgkmcnt(2)
	v_mfma_f32_32x32x16_bf16 v[80:95], v[194:197], v[128:131], v[80:95]
	v_mfma_f32_32x32x16_bf16 v[64:79], v[224:227], v[128:131], v[64:79]
	s_waitcnt lgkmcnt(0)
	v_mfma_f32_32x32x16_bf16 v[80:95], v[228:231], v[136:139], v[80:95]
	v_mfma_f32_32x32x16_bf16 v[64:79], v[232:235], v[136:139], v[64:79]
	s_nop 9
	v_max_f32_e32 v194, v81, v81
	v_max_f32_e32 v195, v80, v80
	v_max_f32_e32 v194, v195, v194
	v_max3_f32 v194, v194, v82, v83
	v_max3_f32 v194, v194, v84, v85
	v_max3_f32 v194, v194, v86, v87
	v_max3_f32 v194, v194, v88, v89
	v_max3_f32 v194, v194, v90, v91
	v_max3_f32 v194, v194, v92, v93
	v_max3_f32 v194, v194, v94, v95
	v_max3_f32 v194, v194, v64, v65
	v_max3_f32 v194, v194, v66, v67
	v_max3_f32 v194, v194, v68, v69
	v_max3_f32 v194, v194, v70, v71
	v_max3_f32 v194, v194, v72, v73
	v_max3_f32 v194, v194, v74, v75
	v_max3_f32 v194, v194, v76, v77
	v_max3_f32 v194, v194, v78, v79
	v_mov_b32_e32 v195, v194
	s_nop 1
	v_permlane32_swap_b32_e32 v194, v195
	v_max_f32_e32 v195, v195, v195
	v_max_f32_e32 v194, v194, v194
	v_max_f32_e32 v194, v194, v195
	v_sub_f32_e32 v196, v194, v220
	v_cmp_ge_f32_e32 vcc, s30, v196
	s_cmp_eq_u64 vcc, exec
	s_cselect_b64 s[8:9], -1, 0
	s_waitcnt lgkmcnt(0)
	s_barrier
	s_cbranch_scc0 .Lslow_b1
	v_mov_b32_e32 v194, 1.0
.Lafter_b1:
	v_mul_f32_e32 v195, 0xbdd53b94, v220
	v_fmamk_f32 v80, v80, 0x3dd53b94, v195
	v_fmamk_f32 v81, v81, 0x3dd53b94, v195
	v_fmamk_f32 v82, v82, 0x3dd53b94, v195
	v_fmamk_f32 v83, v83, 0x3dd53b94, v195
	v_fmamk_f32 v84, v84, 0x3dd53b94, v195
	v_fmamk_f32 v85, v85, 0x3dd53b94, v195
	v_fmamk_f32 v86, v86, 0x3dd53b94, v195
	v_fmamk_f32 v87, v87, 0x3dd53b94, v195
	v_fmamk_f32 v88, v88, 0x3dd53b94, v195
	v_fmamk_f32 v89, v89, 0x3dd53b94, v195
	v_fmamk_f32 v90, v90, 0x3dd53b94, v195
	v_fmamk_f32 v91, v91, 0x3dd53b94, v195
	v_fmamk_f32 v92, v92, 0x3dd53b94, v195
	v_fmamk_f32 v93, v93, 0x3dd53b94, v195
	v_fmamk_f32 v94, v94, 0x3dd53b94, v195
	v_fmamk_f32 v95, v95, 0x3dd53b94, v195
	v_fmamk_f32 v64, v64, 0x3dd53b94, v195
	v_fmamk_f32 v65, v65, 0x3dd53b94, v195
	v_fmamk_f32 v66, v66, 0x3dd53b94, v195
	v_fmamk_f32 v67, v67, 0x3dd53b94, v195
	v_fmamk_f32 v68, v68, 0x3dd53b94, v195
	v_fmamk_f32 v69, v69, 0x3dd53b94, v195
	v_fmamk_f32 v70, v70, 0x3dd53b94, v195
	v_fmamk_f32 v71, v71, 0x3dd53b94, v195
	v_fmamk_f32 v72, v72, 0x3dd53b94, v195
	v_fmamk_f32 v73, v73, 0x3dd53b94, v195
	v_fmamk_f32 v74, v74, 0x3dd53b94, v195
	v_fmamk_f32 v75, v75, 0x3dd53b94, v195
	v_fmamk_f32 v76, v76, 0x3dd53b94, v195
	v_fmamk_f32 v77, v77, 0x3dd53b94, v195
	v_fmamk_f32 v78, v78, 0x3dd53b94, v195
	v_fmac_f32_e32 v195, 0x3dd53b94, v79
	v_exp_f32_e32 v79, v80
	v_exp_f32_e32 v80, v81
	v_exp_f32_e32 v81, v82
	v_exp_f32_e32 v82, v83
	v_exp_f32_e32 v83, v84
	v_exp_f32_e32 v196, v64
	v_add_f32_e32 v64, 0, v79
	v_exp_f32_e32 v84, v85
	v_add_f32_e32 v64, v80, v64
	v_exp_f32_e32 v85, v86
	v_add_f32_e32 v64, v81, v64
	v_exp_f32_e32 v86, v87
	v_add_f32_e32 v64, v82, v64
	v_exp_f32_e32 v87, v88
	v_add_f32_e32 v64, v83, v64
	v_exp_f32_e32 v88, v89
	v_add_f32_e32 v64, v84, v64
	v_exp_f32_e32 v89, v90
	v_add_f32_e32 v64, v85, v64
	v_exp_f32_e32 v90, v91
	v_add_f32_e32 v64, v86, v64
	v_exp_f32_e32 v91, v92
	v_add_f32_e32 v64, v87, v64
	v_exp_f32_e32 v92, v93
	v_add_f32_e32 v64, v88, v64
	v_exp_f32_e32 v93, v94
	v_add_f32_e32 v64, v89, v64
	v_exp_f32_e32 v94, v95
	v_add_f32_e32 v64, v90, v64
	v_add_f32_e32 v64, v91, v64
	v_add_f32_e32 v95, v222, v223
	v_exp_f32_e32 v197, v65
	v_add_f32_e32 v64, v92, v64
	v_fmac_f32_e32 v95, v214, v221
	v_exp_f32_e32 v221, v66
	v_add_f32_e32 v64, v93, v64
	v_exp_f32_e32 v222, v67
	v_add_f32_e32 v64, v94, v64
	v_exp_f32_e32 v223, v68
	v_add_f32_e32 v64, v196, v64
	v_exp_f32_e32 v224, v69
	v_add_f32_e32 v64, v197, v64
	v_exp_f32_e32 v225, v70
	v_add_f32_e32 v64, v221, v64
	v_exp_f32_e32 v226, v71
	v_add_f32_e32 v64, v222, v64
	v_exp_f32_e32 v227, v72
	v_add_f32_e32 v64, v223, v64
	v_exp_f32_e32 v228, v73
	v_add_f32_e32 v64, v224, v64
	v_exp_f32_e32 v229, v74
	v_add_f32_e32 v64, v225, v64
	v_exp_f32_e32 v230, v75
	v_add_f32_e32 v64, v226, v64
	v_exp_f32_e32 v231, v76
	v_add_f32_e32 v64, v227, v64
	v_exp_f32_e32 v232, v77
	v_add_f32_e32 v64, v228, v64
	v_exp_f32_e32 v233, v78
	v_add_f32_e32 v64, v229, v64
; #define SBAR() __builtin_amdgcn_sched_barrier(0)
; __device__ __forceinline__ void finishSM(f32x16& p0, f32x16& p1, float alpha, float& l_reg, bf16x8& pa0, bf16x8& pa1, bf16x8& pa2, bf16x8& pa3) {
; #pragma unroll
;   for (int r = 0; r < 16; ++r) p1[r] = __builtin_amdgcn_exp2f(p1[r]);
;   float ps = 0;
; #pragma unroll
;   for (int r = 0; r < 16; ++r) ps += p0[r];
; #pragma unroll
;   for (int r = 0; r < 16; ++r) ps += p1[r];
;   { auto rr = __builtin_amdgcn_permlane32_swap(__float_as_uint(ps), __float_as_uint(ps), false, false);
;     ps = __uint_as_float(rr[0]) + __uint_as_float(rr[1]); }
;   l_reg = l_reg * alpha + ps;
;     ...
;   PK4(p0, 0, pa0); PK4(p0, 8, pa1); PK4(p1, 0, pa2); PK4(p1, 8, pa3);
; __device__ __forceinline__ void pv2(f32x16* o, int vb, bf16x8 pa0, bf16x8 pa1, bf16x8 pa2, bf16x8 pa3) {
;   VSet X, Y;
;   SBAR(); v_issue<0>(X, vb); v_issue<1>(Y, vb);
;   asm volatile("s_waitcnt lgkmcnt(8)" ::: "memory"); SBAR(); v_mma(o[0], X, pa0, pa1, pa2, pa3); SBAR();
;   v_issue<2>(X, vb);
;   asm volatile("s_waitcnt lgkmcnt(8)" ::: "memory"); SBAR(); v_mma(o[1], Y, pa0, pa1, pa2, pa3); SBAR();
;   v_issue<3>(Y, vb);
;   asm volatile("s_waitcnt lgkmcnt(8)" ::: "memory"); SBAR(); v_mma(o[2], X, pa0, pa1, pa2, pa3); SBAR();
;   asm volatile("s_waitcnt lgkmcnt(0)" ::: "memory"); SBAR(); v_mma(o[3], Y, pa0, pa1, pa2, pa3); SBAR();
; }
	v_exp_f32_e32 v195, v195
	v_add_f32_e32 v64, v230, v64
	v_add_f32_e32 v64, v231, v64
	v_add_f32_e32 v64, v232, v64
	v_add_f32_e32 v64, v233, v64
	v_add_f32_e32 v64, v195, v64
	v_mov_b32_e32 v65, v64
	s_nop 1
	v_permlane32_swap_b32_e32 v64, v65
	v_add_f32_e32 v214, v64, v65
	v_fmac_f32_e32 v214, v95, v194
	v_cvt_pk_bf16_f32 v64, v79, v80
	v_cvt_pk_bf16_f32 v65, v81, v82
	v_cvt_pk_bf16_f32 v66, v83, v84
	v_cvt_pk_bf16_f32 v67, v85, v86
	v_cvt_pk_bf16_f32 v68, v87, v88
	v_cvt_pk_bf16_f32 v69, v89, v90
	v_cvt_pk_bf16_f32 v70, v91, v92
	v_cvt_pk_bf16_f32 v71, v93, v94
	v_cvt_pk_bf16_f32 v72, v196, v197
	v_cvt_pk_bf16_f32 v73, v221, v222
	v_cvt_pk_bf16_f32 v74, v223, v224
	v_cvt_pk_bf16_f32 v75, v225, v226
	v_cvt_pk_bf16_f32 v76, v227, v228
	v_cvt_pk_bf16_f32 v77, v229, v230
	v_cvt_pk_bf16_f32 v78, v231, v232
	v_cvt_pk_bf16_f32 v79, v233, v195
	s_nop 0
	v_permlane32_swap_b32_e32 v64, v66
	v_permlane32_swap_b32_e32 v65, v67
	v_permlane32_swap_b32_e32 v68, v70
	v_permlane32_swap_b32_e32 v69, v71
	v_permlane32_swap_b32_e32 v72, v74
	v_permlane32_swap_b32_e32 v73, v75
	v_permlane32_swap_b32_e32 v76, v78
	v_permlane32_swap_b32_e32 v77, v79
	ds_read_b64_tr_b16 v[80:81], v215 offset:0
	ds_read_b64_tr_b16 v[82:83], v215 offset:0x800
	ds_read_b64_tr_b16 v[84:85], v215 offset:0x1000
	ds_read_b64_tr_b16 v[86:87], v215 offset:0x1800
	ds_read_b64_tr_b16 v[88:89], v215 offset:0x2000
	ds_read_b64_tr_b16 v[90:91], v215 offset:0x2800
	ds_read_b64_tr_b16 v[92:93], v215 offset:0x3000
	ds_read_b64_tr_b16 v[94:95], v215 offset:0x3800
	ds_read_b64_tr_b16 v[194:195], v215 offset:0x200
	ds_read_b64_tr_b16 v[196:197], v215 offset:0xa00
	ds_read_b64_tr_b16 v[222:223], v215 offset:0x1200
	ds_read_b64_tr_b16 v[224:225], v215 offset:0x1a00
	ds_read_b64_tr_b16 v[226:227], v215 offset:0x2200
	ds_read_b64_tr_b16 v[228:229], v215 offset:0x2a00
	ds_read_b64_tr_b16 v[230:231], v215 offset:0x3200
	ds_read_b64_tr_b16 v[232:233], v215 offset:0x3a00
	s_waitcnt lgkmcnt(8)
	s_nop 0
	s_nop 0
	v_mfma_f32_32x32x16_bf16 v[0:15], v[64:67], v[80:83], v[0:15]
	v_mfma_f32_32x32x16_bf16 v[0:15], v[68:71], v[84:87], v[0:15]
	v_mfma_f32_32x32x16_bf16 v[0:15], v[72:75], v[88:91], v[0:15]
	v_mfma_f32_32x32x16_bf16 v[0:15], v[76:79], v[92:95], v[0:15]
	ds_read_b64_tr_b16 v[80:81], v215 offset:0x400
	ds_read_b64_tr_b16 v[82:83], v215 offset:0xc00
	ds_read_b64_tr_b16 v[84:85], v215 offset:0x1400
	ds_read_b64_tr_b16 v[86:87], v215 offset:0x1c00
	ds_read_b64_tr_b16 v[88:89], v215 offset:0x2400
	ds_read_b64_tr_b16 v[90:91], v215 offset:0x2c00
	ds_read_b64_tr_b16 v[92:93], v215 offset:0x3400
	ds_read_b64_tr_b16 v[94:95], v215 offset:0x3c00
	s_waitcnt lgkmcnt(8)
	s_nop 0
	v_mfma_f32_32x32x16_bf16 v[48:63], v[64:67], v[194:197], v[48:63]
	v_mfma_f32_32x32x16_bf16 v[48:63], v[68:71], v[222:225], v[48:63]
	v_mfma_f32_32x32x16_bf16 v[48:63], v[72:75], v[226:229], v[48:63]
	v_mfma_f32_32x32x16_bf16 v[48:63], v[76:79], v[230:233], v[48:63]
	ds_read_b64_tr_b16 v[194:195], v215 offset:0x600
	ds_read_b64_tr_b16 v[196:197], v215 offset:0xe00
	ds_read_b64_tr_b16 v[222:223], v215 offset:0x1600
	ds_read_b64_tr_b16 v[224:225], v215 offset:0x1e00
	ds_read_b64_tr_b16 v[226:227], v215 offset:0x2600
	ds_read_b64_tr_b16 v[228:229], v215 offset:0x2e00
	ds_read_b64_tr_b16 v[230:231], v215 offset:0x3600
	ds_read_b64_tr_b16 v[232:233], v215 offset:0x3e00
	s_waitcnt lgkmcnt(8)
	s_nop 0
	v_mfma_f32_32x32x16_bf16 v[32:47], v[64:67], v[80:83], v[32:47]
	v_mfma_f32_32x32x16_bf16 v[32:47], v[68:71], v[84:87], v[32:47]
	v_mfma_f32_32x32x16_bf16 v[32:47], v[72:75], v[88:91], v[32:47]
	v_mfma_f32_32x32x16_bf16 v[32:47], v[76:79], v[92:95], v[32:47]
	s_waitcnt lgkmcnt(0)
	s_nop 0
	v_mfma_f32_32x32x16_bf16 v[16:31], v[64:67], v[194:197], v[16:31]
	v_mfma_f32_32x32x16_bf16 v[16:31], v[68:71], v[222:225], v[16:31]
	v_mfma_f32_32x32x16_bf16 v[16:31], v[72:75], v[226:229], v[16:31]
	v_mfma_f32_32x32x16_bf16 v[16:31], v[76:79], v[230:233], v[16:31]
	s_waitcnt lgkmcnt(0)
	s_barrier
	s_add_i32 s0, s44, 2
	s_add_i32 s1, s44, 3
	s_add_i32 s42, s42, -2
	v_lshl_add_u64 v[190:191], v[190:191], 0, s[14:15]
	s_cmpk_gt_u32 s1, 0x100
	v_lshl_add_u64 v[192:193], v[192:193], 0, s[16:17]
	s_cbranch_scc1 .LBB0_453
	s_mov_b32 s44, s0
	s_branch .LBB0_441
; __device__ __forceinline__ void partialSM(f32x16& p0, f32x16& p1, float& m_reg, float& mn, float& alpha) {
;     ...
;   if (__builtin_expect(__all(pmax - m_reg <= THR / SCALE), 1)) { mn = m_reg; alpha = 1.f; }
;   else { mn = fmaxf(m_reg, pmax); alpha = __builtin_amdgcn_exp2f((m_reg - mn) * C); m_reg = mn; }
.Lslow_b1:
	v_max_f32_e32 v195, v220, v194
	v_sub_f32_e32 v194, v220, v195
	v_mul_f32_e32 v194, 0x3dd53b94, v194
	v_exp_f32_e32 v194, v194
	s_nop 0
	v_cndmask_b32_e64 v194, v194, 1.0, s[8:9]
	v_cmp_gt_f32_e32 vcc, 1.0, v194
	s_cbranch_vccz .LBB0_451
	s_and_saveexec_b64 s[0:1], s[6:7]
	ds_write_b32 v205, v194 offset:128
	s_or_b64 exec, exec, s[0:1]
	s_waitcnt lgkmcnt(0)
	v_add_u32_e32 v196, s3, v184
	ds_read_b128 v[224:227], v196 offset:224
	ds_read_b128 v[228:231], v196 offset:192
	ds_read_b128 v[232:235], v196 offset:160
	ds_read_b128 v[236:239], v196 offset:128
	s_waitcnt lgkmcnt(3)
	v_pk_mul_f32 v[12:13], v[12:13], v[224:225]
	s_waitcnt lgkmcnt(2)
	v_pk_mul_f32 v[8:9], v[8:9], v[228:229]
	s_waitcnt lgkmcnt(1)
	v_pk_mul_f32 v[4:5], v[4:5], v[232:233]
	v_pk_mul_f32 v[14:15], v[14:15], v[226:227]
	v_pk_mul_f32 v[10:11], v[10:11], v[230:231]
	v_pk_mul_f32 v[6:7], v[6:7], v[234:235]
	s_waitcnt lgkmcnt(0)
	v_pk_mul_f32 v[2:3], v[2:3], v[238:239]
	v_pk_mul_f32 v[0:1], v[0:1], v[236:237]
	v_pk_mul_f32 v[60:61], v[60:61], v[224:225]
	v_pk_mul_f32 v[56:57], v[56:57], v[228:229]
	v_pk_mul_f32 v[52:53], v[52:53], v[232:233]
	v_pk_mul_f32 v[62:63], v[62:63], v[226:227]
	v_pk_mul_f32 v[58:59], v[58:59], v[230:231]
	v_pk_mul_f32 v[54:55], v[54:55], v[234:235]
	v_pk_mul_f32 v[50:51], v[50:51], v[238:239]
	v_pk_mul_f32 v[48:49], v[48:49], v[236:237]
	v_pk_mul_f32 v[44:45], v[44:45], v[224:225]
	v_pk_mul_f32 v[40:41], v[40:41], v[228:229]
	v_pk_mul_f32 v[36:37], v[36:37], v[232:233]
	v_pk_mul_f32 v[46:47], v[46:47], v[226:227]
	v_pk_mul_f32 v[42:43], v[42:43], v[230:231]
	v_pk_mul_f32 v[38:39], v[38:39], v[234:235]
	v_pk_mul_f32 v[34:35], v[34:35], v[238:239]
	v_pk_mul_f32 v[32:33], v[32:33], v[236:237]
	v_pk_mul_f32 v[28:29], v[28:29], v[224:225]
	v_pk_mul_f32 v[24:25], v[24:25], v[228:229]
	v_pk_mul_f32 v[20:21], v[20:21], v[232:233]
	v_pk_mul_f32 v[30:31], v[30:31], v[226:227]
	v_pk_mul_f32 v[26:27], v[26:27], v[230:231]
	v_pk_mul_f32 v[22:23], v[22:23], v[234:235]
	v_pk_mul_f32 v[18:19], v[18:19], v[238:239]
	v_pk_mul_f32 v[16:17], v[16:17], v[236:237]
.LBB0_451:
	v_cndmask_b32_e64 v220, v195, v220, s[8:9]
	s_branch .Lafter_b1
.Lslow_b0:
	v_max_f32_e32 v90, v220, v144
	v_sub_f32_e32 v92, v220, v90
	v_mul_f32_e32 v92, 0x3dd53b94, v92
	v_exp_f32_e32 v92, v92
	s_nop 0
	v_cndmask_b32_e64 v221, v92, 1.0, s[8:9]
	v_cmp_gt_f32_e32 vcc, 1.0, v221
	s_cbranch_vccz .LBB0_445
	s_and_saveexec_b64 s[0:1], s[6:7]
	ds_write_b32 v205, v221 offset:128
	s_or_b64 exec, exec, s[0:1]
	s_waitcnt lgkmcnt(0)
	v_add_u32_e32 v91, s3, v184
	ds_read_b128 v[92:95], v91 offset:224
	ds_read_b128 v[228:231], v91 offset:192
	ds_read_b128 v[232:235], v91 offset:160
	ds_read_b128 v[236:239], v91 offset:128
	s_waitcnt lgkmcnt(3)
	v_pk_mul_f32 v[12:13], v[12:13], v[92:93]
	s_waitcnt lgkmcnt(2)
	v_pk_mul_f32 v[8:9], v[8:9], v[228:229]
	s_waitcnt lgkmcnt(1)
	v_pk_mul_f32 v[4:5], v[4:5], v[232:233]
	v_pk_mul_f32 v[14:15], v[14:15], v[94:95]
	v_pk_mul_f32 v[10:11], v[10:11], v[230:231]
	v_pk_mul_f32 v[6:7], v[6:7], v[234:235]
	s_waitcnt lgkmcnt(0)
	v_pk_mul_f32 v[2:3], v[2:3], v[238:239]
	v_pk_mul_f32 v[0:1], v[0:1], v[236:237]
	v_pk_mul_f32 v[60:61], v[60:61], v[92:93]
	v_pk_mul_f32 v[56:57], v[56:57], v[228:229]
	v_pk_mul_f32 v[52:53], v[52:53], v[232:233]
	v_pk_mul_f32 v[62:63], v[62:63], v[94:95]
	v_pk_mul_f32 v[58:59], v[58:59], v[230:231]
	v_pk_mul_f32 v[54:55], v[54:55], v[234:235]
	v_pk_mul_f32 v[50:51], v[50:51], v[238:239]
	v_pk_mul_f32 v[48:49], v[48:49], v[236:237]
	v_pk_mul_f32 v[44:45], v[44:45], v[92:93]
	v_pk_mul_f32 v[40:41], v[40:41], v[228:229]
	v_pk_mul_f32 v[36:37], v[36:37], v[232:233]
	v_pk_mul_f32 v[46:47], v[46:47], v[94:95]
	v_pk_mul_f32 v[42:43], v[42:43], v[230:231]
	v_pk_mul_f32 v[38:39], v[38:39], v[234:235]
	v_pk_mul_f32 v[34:35], v[34:35], v[238:239]
	v_pk_mul_f32 v[32:33], v[32:33], v[236:237]
	v_pk_mul_f32 v[28:29], v[28:29], v[92:93]
	v_pk_mul_f32 v[24:25], v[24:25], v[228:229]
	v_pk_mul_f32 v[20:21], v[20:21], v[232:233]
	v_pk_mul_f32 v[30:31], v[30:31], v[94:95]
	v_pk_mul_f32 v[26:27], v[26:27], v[230:231]
	v_pk_mul_f32 v[22:23], v[22:23], v[234:235]
	v_pk_mul_f32 v[18:19], v[18:19], v[238:239]
	v_pk_mul_f32 v[16:17], v[16:17], v[236:237]
.LBB0_445:
	v_cndmask_b32_e64 v220, v90, v220, s[8:9]
	s_branch .Lafter_b0

; __device__ __forceinline__ void partialSM(f32x16& p0, f32x16& p1, float& m_reg, float& mn, float& alpha) {
;   constexpr float C = SCALE * 1.4426950408889634f;
;   float pmax = p0[0];
; #pragma unroll
;   for (int r = 1; r < 16; ++r) pmax = fmaxf(pmax, p0[r]);
; #pragma unroll
;   for (int r = 0; r < 16; ++r) pmax = fmaxf(pmax, p1[r]);
;   { auto rr = __builtin_amdgcn_permlane32_swap(__float_as_uint(pmax), __float_as_uint(pmax), false, false);
;     pmax = fmaxf(__uint_as_float(rr[0]), __uint_as_float(rr[1])); }
;   if (__builtin_expect(__all(pmax - m_reg <= THR / SCALE), 1)) { mn = m_reg; alpha = 1.f; }
;   else { mn = fmaxf(m_reg, pmax); alpha = __builtin_amdgcn_exp2f((m_reg - mn) * C); m_reg = mn; }
;   float mnC = -mn * C;
; #pragma unroll
;   for (int r = 0; r < 16; ++r) p0[r] = fmaf(p0[r], C, mnC);
; #pragma unroll
;   for (int r = 0; r < 16; ++r) p1[r] = fmaf(p1[r], C, mnC);
; #pragma unroll
;   for (int r = 0; r < 16; ++r) p0[r] = __builtin_amdgcn_exp2f(p0[r]);
; }
; __device__ __forceinline__ void finishSM(f32x16& p0, f32x16& p1, float alpha, float& l_reg, bf16x8& pa0, bf16x8& pa1, bf16x8& pa2, bf16x8& pa3) {
; #pragma unroll
;   for (int r = 0; r < 16; ++r) p1[r] = __builtin_amdgcn_exp2f(p1[r]);
;   float ps = 0;
; #pragma unroll
;   for (int r = 0; r < 16; ++r) ps += p0[r];
; #pragma unroll
;   for (int r = 0; r < 16; ++r) ps += p1[r];
;   { auto rr = __builtin_amdgcn_permlane32_swap(__float_as_uint(ps), __float_as_uint(ps), false, false);
;     ps = __uint_as_float(rr[0]) + __uint_as_float(rr[1]); }
;   l_reg = l_reg * alpha + ps;
;     ...
;   PK4(p0, 0, pa0); PK4(p0, 8, pa1); PK4(p1, 0, pa2); PK4(p1, 8, pa3);
.Lback0_a:
	v_max3_f32 v248, v64, v65, v66
	v_max3_f32 v249, v80, v81, v82
	v_max3_f32 v248, v248, v67, v68
	v_max3_f32 v249, v249, v83, v84
	v_max3_f32 v248, v248, v69, v70
	v_max3_f32 v249, v249, v85, v86
	v_max3_f32 v248, v248, v71, v72
	v_max3_f32 v249, v249, v87, v88
	v_max3_f32 v248, v248, v73, v74
	v_max3_f32 v249, v249, v89, v90
	v_max3_f32 v248, v248, v75, v76
	v_max3_f32 v249, v249, v91, v92
	v_max3_f32 v248, v248, v77, v78
	v_max3_f32 v249, v249, v93, v94
	v_max3_f32 v248, v248, v79, v95
	v_max_f32_e32 v248, v248, v249
	v_mov_b32_e32 v249, v248
	s_nop 1
	v_permlane32_swap_b32_e32 v248, v249
	v_max_f32_e32 v248, v248, v249
	v_sub_f32_e32 v249, v248, v178
	v_cmp_ge_f32_e32 vcc, s30, v249
	s_cmp_eq_u64 vcc, exec
	s_cselect_b64 s[8:9], -1, 0
	s_waitcnt lgkmcnt(0)
	s_barrier
	s_waitcnt vmcnt(0)
	ds_write_b128 v212, v[144:147] offset:16384
	ds_write_b128 v212, v[148:151] offset:17408
	ds_write_b128 v211, v[152:155] offset:57344
	ds_write_b128 v211, v[156:159] offset:57472
	ds_write_b128 v211, v[160:163] offset:57600
	v_lshl_add_u64 v[170:171], s[52:53], 0, v[166:167]
	v_add_co_u32_e32 v148, vcc, s28, v170
	v_lshl_add_u64 v[168:169], s[52:53], 0, v[164:165]
	s_nop 0
	v_addc_co_u32_e32 v149, vcc, 0, v171, vcc
	v_add_co_u32_e32 v160, vcc, 0x1b330000, v168
	global_load_dwordx4 v[144:147], v[148:149], off offset:256
	s_nop 0
	global_load_dwordx4 v[148:151], v[148:149], off offset:384
	v_addc_co_u32_e32 v161, vcc, 0, v169, vcc
	global_load_dwordx4 v[152:155], v[160:161], off
	global_load_dwordx4 v[156:159], v[160:161], off offset:128
	s_nop 0
	global_load_dwordx4 v[160:163], v[160:161], off offset:256
	v_mov_b32_e32 v180, v76
	v_mov_b32_e32 v181, v77
	v_mov_b32_e32 v76, v90
	v_mov_b32_e32 v77, v91
	v_mov_b32_e32 v186, v72
	v_mov_b32_e32 v187, v73
	v_mov_b32_e32 v182, v74
	v_mov_b32_e32 v183, v75
	v_mov_b32_e32 v74, v92
	v_mov_b32_e32 v75, v93
	v_mov_b32_e32 v73, v94
	v_mov_b32_e32 v72, v95
	s_cbranch_scc0 .Lslow_a0
	v_mov_b32_e32 v179, 1.0
.Lafter_a0:
	v_mul_f32_e32 v90, 0xbdd53b94, v178
	v_fmamk_f32 v64, v64, 0x3dd53b94, v90
	v_fmamk_f32 v65, v65, 0x3dd53b94, v90
	v_exp_f32_e32 v64, v64
	v_fmamk_f32 v66, v66, 0x3dd53b94, v90
	v_exp_f32_e32 v65, v65
	v_fmamk_f32 v67, v67, 0x3dd53b94, v90
	v_exp_f32_e32 v66, v66
	v_fmamk_f32 v68, v68, 0x3dd53b94, v90
	v_fmamk_f32 v73, v73, 0x3dd53b94, v90
	v_exp_f32_e32 v67, v67
	v_fmamk_f32 v69, v69, 0x3dd53b94, v90
	v_fmamk_f32 v92, v187, 0x3dd53b94, v90
	v_exp_f32_e32 v68, v68
	v_exp_f32_e32 v187, v73
	v_add_f32_e32 v73, 0, v64
	v_fmamk_f32 v70, v70, 0x3dd53b94, v90
	v_exp_f32_e32 v69, v69
	v_add_f32_e32 v73, v65, v73
	v_fmamk_f32 v71, v71, 0x3dd53b94, v90
	v_exp_f32_e32 v70, v70
	v_add_f32_e32 v73, v66, v73
	v_fmamk_f32 v91, v186, 0x3dd53b94, v90
	v_exp_f32_e32 v71, v71
	v_add_f32_e32 v73, v67, v73
	v_fmamk_f32 v93, v182, 0x3dd53b94, v90
	v_fmamk_f32 v94, v183, 0x3dd53b94, v90
	v_fmamk_f32 v95, v180, 0x3dd53b94, v90
	v_fmamk_f32 v180, v181, 0x3dd53b94, v90
	v_fmamk_f32 v78, v78, 0x3dd53b94, v90
	v_fmamk_f32 v79, v79, 0x3dd53b94, v90
	v_fmamk_f32 v80, v80, 0x3dd53b94, v90
	v_fmamk_f32 v81, v81, 0x3dd53b94, v90
	v_fmamk_f32 v82, v82, 0x3dd53b94, v90
	v_fmamk_f32 v83, v83, 0x3dd53b94, v90
	v_fmamk_f32 v84, v84, 0x3dd53b94, v90
	v_fmamk_f32 v85, v85, 0x3dd53b94, v90
	v_fmamk_f32 v86, v86, 0x3dd53b94, v90
	v_fmamk_f32 v87, v87, 0x3dd53b94, v90
	v_fmamk_f32 v88, v88, 0x3dd53b94, v90
	v_fmamk_f32 v89, v89, 0x3dd53b94, v90
	v_fmamk_f32 v76, v76, 0x3dd53b94, v90
	v_fmamk_f32 v77, v77, 0x3dd53b94, v90
	v_fmamk_f32 v74, v74, 0x3dd53b94, v90
	v_fmamk_f32 v75, v75, 0x3dd53b94, v90
	v_fmac_f32_e32 v90, 0x3dd53b94, v72
	v_exp_f32_e32 v72, v91
	v_add_f32_e32 v73, v68, v73
	v_exp_f32_e32 v91, v92
	v_add_f32_e32 v73, v69, v73
	v_exp_f32_e32 v92, v93
	v_add_f32_e32 v73, v70, v73
	v_exp_f32_e32 v93, v94
	v_add_f32_e32 v73, v71, v73
	v_exp_f32_e32 v94, v95
	v_add_f32_e32 v73, v72, v73
	v_exp_f32_e32 v95, v180
	v_add_f32_e32 v73, v91, v73
	v_exp_f32_e32 v78, v78
	v_add_f32_e32 v73, v92, v73
	v_exp_f32_e32 v79, v79
	v_add_f32_e32 v73, v93, v73
	v_exp_f32_e32 v80, v80
	v_add_f32_e32 v73, v94, v73
	v_exp_f32_e32 v81, v81
	v_add_f32_e32 v73, v95, v73
	v_exp_f32_e32 v82, v82
	v_add_f32_e32 v73, v78, v73
	v_exp_f32_e32 v83, v83
	v_add_f32_e32 v73, v79, v73
	v_exp_f32_e32 v84, v84
	v_add_f32_e32 v73, v80, v73
	v_exp_f32_e32 v85, v85
	v_add_f32_e32 v73, v81, v73
	v_exp_f32_e32 v86, v86
	v_add_f32_e32 v73, v82, v73
	v_exp_f32_e32 v87, v87
	v_add_f32_e32 v73, v83, v73
	v_exp_f32_e32 v88, v88
	v_add_f32_e32 v73, v84, v73
	v_exp_f32_e32 v89, v89
	v_add_f32_e32 v73, v85, v73
	v_exp_f32_e32 v182, v76
	v_add_f32_e32 v73, v86, v73
	v_exp_f32_e32 v77, v77
	v_add_f32_e32 v73, v87, v73
	v_exp_f32_e32 v183, v74
	v_add_f32_e32 v73, v88, v73
	v_exp_f32_e32 v186, v75
	v_add_f32_e32 v73, v89, v73
	v_add_f32_e32 v73, v182, v73
	v_exp_f32_e32 v90, v90
	v_add_f32_e32 v73, v77, v73
	v_add_f32_e32 v73, v183, v73
	v_add_f32_e32 v73, v186, v73
	v_add_f32_e32 v73, v187, v73
	v_add_f32_e32 v180, v90, v73
	v_mov_b32_e32 v181, v180
	v_cvt_pk_bf16_f32 v64, v64, v65
	v_cvt_pk_bf16_f32 v65, v66, v67
	v_cvt_pk_bf16_f32 v66, v68, v69
	v_cvt_pk_bf16_f32 v67, v70, v71
	v_cvt_pk_bf16_f32 v68, v72, v91
	v_cvt_pk_bf16_f32 v69, v92, v93
	v_cvt_pk_bf16_f32 v70, v94, v95
	v_cvt_pk_bf16_f32 v71, v78, v79
	v_cvt_pk_bf16_f32 v72, v80, v81
	v_cvt_pk_bf16_f32 v73, v82, v83
	v_cvt_pk_bf16_f32 v74, v84, v85
	v_cvt_pk_bf16_f32 v75, v86, v87
	v_cvt_pk_bf16_f32 v76, v88, v89
	v_cvt_pk_bf16_f32 v77, v182, v77
	v_cvt_pk_bf16_f32 v78, v183, v186
	v_cvt_pk_bf16_f32 v79, v187, v90
	s_nop 1
	v_permlane32_swap_b32_e32 v180, v181
	v_permlane32_swap_b32_e32 v64, v66
	v_permlane32_swap_b32_e32 v65, v67
	v_permlane32_swap_b32_e32 v68, v70
	v_permlane32_swap_b32_e32 v69, v71
	v_permlane32_swap_b32_e32 v72, v74
	v_permlane32_swap_b32_e32 v73, v75
	v_permlane32_swap_b32_e32 v76, v78
	v_permlane32_swap_b32_e32 v77, v79
	ds_read_b64_tr_b16 v[80:81], v206 offset:0
	ds_read_b64_tr_b16 v[82:83], v206 offset:0x800
	ds_read_b64_tr_b16 v[84:85], v206 offset:0x1000
	ds_read_b64_tr_b16 v[86:87], v206 offset:0x1800
	ds_read_b64_tr_b16 v[88:89], v206 offset:0x2000
	ds_read_b64_tr_b16 v[90:91], v206 offset:0x2800
	ds_read_b64_tr_b16 v[92:93], v206 offset:0x3000
	ds_read_b64_tr_b16 v[94:95], v206 offset:0x3800
	ds_read_b64_tr_b16 v[186:187], v206 offset:0x200
	ds_read_b64_tr_b16 v[188:189], v206 offset:0xa00
	ds_read_b64_tr_b16 v[190:191], v206 offset:0x1200
	ds_read_b64_tr_b16 v[192:193], v206 offset:0x1a00
	ds_read_b64_tr_b16 v[194:195], v206 offset:0x2200
	ds_read_b64_tr_b16 v[196:197], v206 offset:0x2a00
	ds_read_b64_tr_b16 v[214:215], v206 offset:0x3200
	ds_read_b64_tr_b16 v[216:217], v206 offset:0x3a00
	s_waitcnt lgkmcnt(8)
; __device__ __forceinline__ void partialSM(f32x16& p0, f32x16& p1, float& m_reg, float& mn, float& alpha) {
;   constexpr float C = SCALE * 1.4426950408889634f;
;   float pmax = p0[0];
; #pragma unroll
; __device__ __forceinline__ void qkt2(f32x16& p0, f32x16& p1, const char* Ks, const bf16x8* qr, const int* kb4) {
;     ...
;   p0 = f32x16{}; p1 = f32x16{};
;   bf16x8 a0 = KLD(0, 0), b0 = KLD(0, 1), a1 = KLD(1, 0), b1 = KLD(1, 1), a2, b2;
;     ...
;   QSTEP(0, a0, b0, a2, b2); QSTEP(1, a1, b1, a0, b0); QSTEP(2, a2, b2, a1, b1);
;   QSTEP(3, a0, b0, a2, b2); QSTEP(4, a1, b1, a0, b0); QSTEP(5, a2, b2, a1, b1);
;   QSTEP(6, a0, b0, a2, b2); QSTEP(7, a1, b1, a0, b0); QSTEP(8, a2, b2, a1, b1);
;   QSTEP(9, a0, b0, a2, b2); QSTEP(10, a1, b1, a0, b0); QSTEP(11, a2, b2, a1, b1);
;     ...
; }
; template <int D0> __device__ __forceinline__ void v_issue(VSet& s, int vb) {
;   s.l0 = tr_read<v_rd_off(D0, 0, 0)>(vb); s.h0 = tr_read<v_rd_off(D0, 0, 1)>(vb); s.l1 = tr_read<v_rd_off(D0, 1, 0)>(vb); s.h1 = tr_read<v_rd_off(D0, 1, 1)>(vb);
;   s.l2 = tr_read<v_rd_off(D0, 2, 0)>(vb); s.h2 = tr_read<v_rd_off(D0, 2, 1)>(vb); s.l3 = tr_read<v_rd_off(D0, 3, 0)>(vb); s.h3 = tr_read<v_rd_off(D0, 3, 1)>(vb);
; }
; __device__ __forceinline__ void v_mma(f32x16& od, VSet& s, bf16x8 pa0, bf16x8 pa1, bf16x8 pa2, bf16x8 pa3) {
;   asm volatile("" : "+v"(s.l0), "+v"(s.h0), "+v"(s.l1), "+v"(s.h1), "+v"(s.l2), "+v"(s.h2), "+v"(s.l3), "+v"(s.h3));
;     ...
;   od = __builtin_amdgcn_mfma_f32_32x32x16_bf16(pa0, PK(s.l0, s.h0), od, 0, 0, 0);
;   od = __builtin_amdgcn_mfma_f32_32x32x16_bf16(pa1, PK(s.l1, s.h1), od, 0, 0, 0);
;   od = __builtin_amdgcn_mfma_f32_32x32x16_bf16(pa2, PK(s.l2, s.h2), od, 0, 0, 0);
;   od = __builtin_amdgcn_mfma_f32_32x32x16_bf16(pa3, PK(s.l3, s.h3), od, 0, 0, 0);
;     ...
; }
; __device__ __forceinline__ void pv2(f32x16* o, int vb, bf16x8 pa0, bf16x8 pa1, bf16x8 pa2, bf16x8 pa3) {
;   VSet X, Y;
;   SBAR(); v_issue<0>(X, vb); v_issue<1>(Y, vb);
;   asm volatile("s_waitcnt lgkmcnt(8)" ::: "memory"); SBAR(); v_mma(o[0], X, pa0, pa1, pa2, pa3); SBAR();
;   v_issue<2>(X, vb);
;   asm volatile("s_waitcnt lgkmcnt(8)" ::: "memory"); SBAR(); v_mma(o[1], Y, pa0, pa1, pa2, pa3); SBAR();
;   v_issue<3>(Y, vb);
;   asm volatile("s_waitcnt lgkmcnt(8)" ::: "memory"); SBAR(); v_mma(o[2], X, pa0, pa1, pa2, pa3); SBAR();
;   asm volatile("s_waitcnt lgkmcnt(0)" ::: "memory"); SBAR(); v_mma(o[3], Y, pa0, pa1, pa2, pa3); SBAR();
; }
	s_nop 0
	s_nop 0
	v_mfma_f32_32x32x16_bf16 v[0:15], v[64:67], v[80:83], v[0:15]
	v_mfma_f32_32x32x16_bf16 v[0:15], v[68:71], v[84:87], v[0:15]
	v_mfma_f32_32x32x16_bf16 v[0:15], v[72:75], v[88:91], v[0:15]
	v_mfma_f32_32x32x16_bf16 v[0:15], v[76:79], v[92:95], v[0:15]
	ds_read_b64_tr_b16 v[80:81], v206 offset:0x400
	ds_read_b64_tr_b16 v[82:83], v206 offset:0xc00
	ds_read_b64_tr_b16 v[84:85], v206 offset:0x1400
	ds_read_b64_tr_b16 v[86:87], v206 offset:0x1c00
	ds_read_b64_tr_b16 v[88:89], v206 offset:0x2400
	ds_read_b64_tr_b16 v[90:91], v206 offset:0x2c00
	ds_read_b64_tr_b16 v[92:93], v206 offset:0x3400
	ds_read_b64_tr_b16 v[94:95], v206 offset:0x3c00
	s_waitcnt lgkmcnt(8)
	s_nop 0
	v_mfma_f32_32x32x16_bf16 v[48:63], v[64:67], v[186:189], v[48:63]
	v_mfma_f32_32x32x16_bf16 v[48:63], v[68:71], v[190:193], v[48:63]
	v_mfma_f32_32x32x16_bf16 v[48:63], v[72:75], v[194:197], v[48:63]
	v_mfma_f32_32x32x16_bf16 v[48:63], v[76:79], v[214:217], v[48:63]
	ds_read_b64_tr_b16 v[186:187], v206 offset:0x600
	ds_read_b64_tr_b16 v[188:189], v206 offset:0xe00
	ds_read_b64_tr_b16 v[190:191], v206 offset:0x1600
	ds_read_b64_tr_b16 v[192:193], v206 offset:0x1e00
	ds_read_b64_tr_b16 v[194:195], v206 offset:0x2600
	ds_read_b64_tr_b16 v[196:197], v206 offset:0x2e00
	ds_read_b64_tr_b16 v[214:215], v206 offset:0x3600
	ds_read_b64_tr_b16 v[216:217], v206 offset:0x3e00
	s_waitcnt lgkmcnt(8)
	s_nop 0
	v_mfma_f32_32x32x16_bf16 v[32:47], v[64:67], v[80:83], v[32:47]
	v_mfma_f32_32x32x16_bf16 v[32:47], v[68:71], v[84:87], v[32:47]
	v_mfma_f32_32x32x16_bf16 v[32:47], v[72:75], v[88:91], v[32:47]
	v_mfma_f32_32x32x16_bf16 v[32:47], v[76:79], v[92:95], v[32:47]
	s_waitcnt lgkmcnt(0)
	s_nop 0
	v_mfma_f32_32x32x16_bf16 v[16:31], v[64:67], v[186:189], v[16:31]
	v_mfma_f32_32x32x16_bf16 v[16:31], v[68:71], v[190:193], v[16:31]
	v_mfma_f32_32x32x16_bf16 v[16:31], v[72:75], v[194:197], v[16:31]
	v_mfma_f32_32x32x16_bf16 v[16:31], v[76:79], v[214:217], v[16:31]
	s_waitcnt lgkmcnt(0)
	s_barrier
	ds_read_b128 v[64:67], v174 offset:12288
	ds_read_b128 v[186:189], v175 offset:12288
	ds_read_b128 v[190:193], v209 offset:57344
	ds_read_b128 v[194:197], v208 offset:57344
	ds_read_b128 v[68:71], v210 offset:57344
	ds_read_b128 v[214:217], v176 offset:12288
	s_waitcnt lgkmcnt(1)
	v_mfma_f32_32x32x16_bf16 v[80:95], v[68:71], v[96:99], 0
	v_mfma_f32_32x32x16_bf16 v[64:79], v[64:67], v[96:99], 0
	ds_read_b128 v[218:221], v207 offset:57344
	ds_read_b128 v[222:225], v177 offset:12288
	v_mfma_f32_32x32x16_bf16 v[80:95], v[190:193], v[100:103], v[80:95]
	v_mfma_f32_32x32x16_bf16 v[64:79], v[186:189], v[100:103], v[64:79]
	ds_read_b128 v[186:189], v210 offset:57472
	ds_read_b128 v[190:193], v174 offset:12416
	v_mfma_f32_32x32x16_bf16 v[80:95], v[194:197], v[104:107], v[80:95]
	s_waitcnt lgkmcnt(4)
	v_mfma_f32_32x32x16_bf16 v[64:79], v[214:217], v[104:107], v[64:79]
	ds_read_b128 v[194:197], v209 offset:57472
	ds_read_b128 v[214:217], v175 offset:12416
	s_waitcnt lgkmcnt(4)
	v_mfma_f32_32x32x16_bf16 v[80:95], v[218:221], v[108:111], v[80:95]
	v_mfma_f32_32x32x16_bf16 v[64:79], v[222:225], v[108:111], v[64:79]
	ds_read_b128 v[218:221], v208 offset:57472
	ds_read_b128 v[222:225], v176 offset:12416
	s_waitcnt lgkmcnt(4)
	v_mfma_f32_32x32x16_bf16 v[80:95], v[186:189], v[112:115], v[80:95]
	v_mfma_f32_32x32x16_bf16 v[64:79], v[190:193], v[112:115], v[64:79]
	ds_read_b128 v[186:189], v207 offset:57472
	ds_read_b128 v[190:193], v177 offset:12416
	s_waitcnt lgkmcnt(4)
	v_mfma_f32_32x32x16_bf16 v[80:95], v[194:197], v[116:119], v[80:95]
	v_mfma_f32_32x32x16_bf16 v[64:79], v[214:217], v[116:119], v[64:79]
	ds_read_b128 v[194:197], v210 offset:57600
	ds_read_b128 v[214:217], v174 offset:12544
	s_waitcnt lgkmcnt(4)
	v_mfma_f32_32x32x16_bf16 v[80:95], v[218:221], v[120:123], v[80:95]
	v_mfma_f32_32x32x16_bf16 v[64:79], v[222:225], v[120:123], v[64:79]
	ds_read_b128 v[218:221], v209 offset:57600
	ds_read_b128 v[222:225], v175 offset:12544
	s_waitcnt lgkmcnt(4)
	v_mfma_f32_32x32x16_bf16 v[80:95], v[186:189], v[124:127], v[80:95]
	v_mfma_f32_32x32x16_bf16 v[64:79], v[190:193], v[124:127], v[64:79]
	ds_read_b128 v[186:189], v208 offset:57600
	ds_read_b128 v[190:193], v176 offset:12544
	s_waitcnt lgkmcnt(4)
	v_mfma_f32_32x32x16_bf16 v[80:95], v[194:197], v[132:135], v[80:95]
	v_mfma_f32_32x32x16_bf16 v[64:79], v[214:217], v[132:135], v[64:79]
	ds_read_b128 v[194:197], v207 offset:57600
	ds_read_b128 v[214:217], v177 offset:12544
	s_waitcnt lgkmcnt(4)
	v_mfma_f32_32x32x16_bf16 v[80:95], v[218:221], v[140:143], v[80:95]
	v_mfma_f32_32x32x16_bf16 v[64:79], v[222:225], v[140:143], v[64:79]
	s_waitcnt lgkmcnt(2)
	v_mfma_f32_32x32x16_bf16 v[80:95], v[186:189], v[128:131], v[80:95]
	v_mfma_f32_32x32x16_bf16 v[64:79], v[190:193], v[128:131], v[64:79]
	s_waitcnt lgkmcnt(0)
	v_mfma_f32_32x32x16_bf16 v[80:95], v[194:197], v[136:139], v[80:95]
	v_mfma_f32_32x32x16_bf16 v[64:79], v[214:217], v[136:139], v[64:79]
	s_nop 9
	v_max_f32_e32 v182, v81, v81
	v_max_f32_e32 v183, v80, v80
	v_max_f32_e32 v182, v183, v182
	v_max3_f32 v182, v182, v82, v83
	v_max3_f32 v182, v182, v84, v85
	v_max3_f32 v182, v182, v86, v87
	v_max3_f32 v182, v182, v88, v89
	v_max3_f32 v182, v182, v90, v91
	v_max3_f32 v182, v182, v92, v93
	v_max3_f32 v182, v182, v94, v95
	v_max3_f32 v182, v182, v64, v65
	v_max3_f32 v182, v182, v66, v67
	v_max3_f32 v182, v182, v68, v69
	v_max3_f32 v182, v182, v70, v71
	v_max3_f32 v182, v182, v72, v73
	v_max3_f32 v182, v182, v74, v75
	v_max3_f32 v182, v182, v76, v77
	v_max3_f32 v182, v182, v78, v79
	v_mov_b32_e32 v183, v182
	s_nop 1
	v_permlane32_swap_b32_e32 v182, v183
	v_max_f32_e32 v183, v183, v183
	v_max_f32_e32 v182, v182, v182
	s_waitcnt lgkmcnt(0)
	s_barrier
	v_max_f32_e32 v182, v182, v183
	s_waitcnt vmcnt(0)
	v_sub_f32_e32 v183, v182, v178
	v_cmp_ge_f32_e64 s[8:9], s30, v183
	s_cmpk_gt_u32 s19, 0xfd
	ds_write_b128 v212, v[144:147]
	ds_write_b128 v212, v[148:151] offset:1024
	ds_write_b128 v211, v[152:155] offset:32768
	ds_write_b128 v211, v[156:159] offset:32896
	ds_write_b128 v211, v[160:163] offset:33024
	s_cbranch_scc1 .LBB0_465
	v_add_co_u32_e32 v148, vcc, 0x28780000, v170
	s_nop 1
	v_addc_co_u32_e32 v149, vcc, 0, v171, vcc
	v_add_co_u32_e32 v160, vcc, 0x1b360000, v168
	global_load_dwordx4 v[144:147], v[148:149], off offset:256
	s_nop 0
	global_load_dwordx4 v[148:151], v[148:149], off offset:384
	v_addc_co_u32_e32 v161, vcc, 0, v169, vcc
	global_load_dwordx4 v[152:155], v[160:161], off
	global_load_dwordx4 v[156:159], v[160:161], off offset:128
	s_nop 0
	global_load_dwordx4 v[160:163], v[160:161], off offset:256

; __device__ __forceinline__ void partialSM(f32x16& p0, f32x16& p1, float& m_reg, float& mn, float& alpha) {
;     ...
;   if (__builtin_expect(__all(pmax - m_reg <= THR / SCALE), 1)) { mn = m_reg; alpha = 1.f; }
;   else { mn = fmaxf(m_reg, pmax); alpha = __builtin_amdgcn_exp2f((m_reg - mn) * C); m_reg = mn; }
.Lslow_a0:
	v_max_f32_e32 v90, v178, v248
	v_sub_f32_e32 v92, v178, v90
	v_mul_f32_e32 v92, 0x3dd53b94, v92
	v_exp_f32_e32 v92, v92
	s_nop 0
	v_cndmask_b32_e64 v179, v92, 1.0, s[8:9]
	v_cmp_gt_f32_e32 vcc, 1.0, v179
	s_cbranch_vccz .LBB0_463
	s_and_saveexec_b64 s[0:1], s[6:7]
	ds_write_b32 v205, v179 offset:128
	s_or_b64 exec, exec, s[0:1]
	s_waitcnt lgkmcnt(0)
	v_add_u32_e32 v91, s3, v184
	ds_read_b128 v[92:95], v91 offset:224
	ds_read_b128 v[188:191], v91 offset:192
	ds_read_b128 v[192:195], v91 offset:160
	ds_read_b128 v[214:217], v91 offset:128
	s_waitcnt lgkmcnt(3)
	v_pk_mul_f32 v[12:13], v[12:13], v[92:93]
	s_waitcnt lgkmcnt(2)
	v_pk_mul_f32 v[8:9], v[8:9], v[188:189]
	s_waitcnt lgkmcnt(1)
	v_pk_mul_f32 v[4:5], v[4:5], v[192:193]
	v_pk_mul_f32 v[14:15], v[14:15], v[94:95]
	v_pk_mul_f32 v[10:11], v[10:11], v[190:191]
	v_pk_mul_f32 v[6:7], v[6:7], v[194:195]
	s_waitcnt lgkmcnt(0)
	v_pk_mul_f32 v[2:3], v[2:3], v[216:217]
	v_pk_mul_f32 v[0:1], v[0:1], v[214:215]
	v_pk_mul_f32 v[60:61], v[60:61], v[92:93]
	v_pk_mul_f32 v[56:57], v[56:57], v[188:189]
	v_pk_mul_f32 v[52:53], v[52:53], v[192:193]
	v_pk_mul_f32 v[62:63], v[62:63], v[94:95]
	v_pk_mul_f32 v[58:59], v[58:59], v[190:191]
	v_pk_mul_f32 v[54:55], v[54:55], v[194:195]
	v_pk_mul_f32 v[50:51], v[50:51], v[216:217]
	v_pk_mul_f32 v[48:49], v[48:49], v[214:215]
	v_pk_mul_f32 v[44:45], v[44:45], v[92:93]
	v_pk_mul_f32 v[40:41], v[40:41], v[188:189]
	v_pk_mul_f32 v[36:37], v[36:37], v[192:193]
	v_pk_mul_f32 v[46:47], v[46:47], v[94:95]
	v_pk_mul_f32 v[42:43], v[42:43], v[190:191]
	v_pk_mul_f32 v[38:39], v[38:39], v[194:195]
	v_pk_mul_f32 v[34:35], v[34:35], v[216:217]
	v_pk_mul_f32 v[32:33], v[32:33], v[214:215]
	v_pk_mul_f32 v[28:29], v[28:29], v[92:93]
	v_pk_mul_f32 v[24:25], v[24:25], v[188:189]
	v_pk_mul_f32 v[20:21], v[20:21], v[192:193]
	v_pk_mul_f32 v[30:31], v[30:31], v[94:95]
	v_pk_mul_f32 v[26:27], v[26:27], v[190:191]
	v_pk_mul_f32 v[22:23], v[22:23], v[194:195]
	v_pk_mul_f32 v[18:19], v[18:19], v[216:217]
	v_pk_mul_f32 v[16:17], v[16:17], v[214:215]
.LBB0_463:
	v_cndmask_b32_e64 v178, v90, v178, s[8:9]
	s_branch .Lafter_a0
